# conv tile output stored write-through (agent scope) so the conv arrival needs no L2 writeback
# speedup vs baseline: 1.0041x; 1.0041x over previous
.LBB0_344:
	s_or_b64 exec, exec, s[40:41]
	s_waitcnt lgkmcnt(0)
	s_barrier
	flat_load_dwordx2 v[140:141], v[74:75]
	flat_load_dwordx2 v[142:143], v[76:77]
	v_mov_b32_e32 v144, s43
	ds_read_b64 v[144:145], v144
	s_lshl_b64 s[22:23], s[36:37], 11
	v_mov_b32_e32 v148, s44
	s_add_i32 s78, s78, s3
	s_waitcnt lgkmcnt(0)
	v_pk_add_f32 v[6:7], v[6:7], v[144:145] op_sel_hi:[1,0] neg_lo:[0,1] neg_hi:[0,1]
	s_nop 0
	v_pk_mul_f32 v[6:7], v[144:145], v[6:7] op_sel:[1,0]
	s_waitcnt vmcnt(0)
	v_pk_fma_f32 v[6:7], v[140:141], v[6:7], v[142:143]
	s_nop 0
	v_mul_f32_e32 v144, 0xbfb8aa3b, v6
	v_mul_f32_e32 v145, 0xbfb8aa3b, v7
	v_exp_f32_e32 v144, v144
	v_exp_f32_e32 v145, v145
	v_add_f32_e32 v144, 1.0, v144
	v_add_f32_e32 v145, 1.0, v145
	v_rcp_f32_e32 v146, v144
	v_rcp_f32_e32 v147, v145
	v_lshl_add_u64 v[144:145], v[78:79], 0, s[22:23]
	s_add_i32 s22, s36, 1
	v_mul_f32_e32 v6, v6, v146
	v_mul_f32_e32 v7, v7, v147
	v_cvt_pk_bf16_f32 v6, v6, v7
	flat_store_dword v[144:145], v6 sc1
	ds_read_b64 v[6:7], v148
	s_ashr_i32 s23, s22, 31
	s_lshl_b64 s[22:23], s[22:23], 11
	v_mov_b32_e32 v144, s45
	s_waitcnt lgkmcnt(0)
	v_pk_add_f32 v[4:5], v[4:5], v[6:7] op_sel_hi:[1,0] neg_lo:[0,1] neg_hi:[0,1]
	s_nop 0
	v_pk_mul_f32 v[4:5], v[6:7], v[4:5] op_sel:[1,0]
	s_nop 0
	v_pk_fma_f32 v[4:5], v[140:141], v[4:5], v[142:143]
	s_nop 0
	v_mul_f32_e32 v6, 0xbfb8aa3b, v4
	v_mul_f32_e32 v7, 0xbfb8aa3b, v5
	v_exp_f32_e32 v6, v6
	v_exp_f32_e32 v7, v7
	v_add_f32_e32 v6, 1.0, v6
	v_add_f32_e32 v7, 1.0, v7
	v_rcp_f32_e32 v145, v6
	v_rcp_f32_e32 v146, v7
	v_lshl_add_u64 v[6:7], v[78:79], 0, s[22:23]
	s_add_i32 s22, s36, 2
	v_mul_f32_e32 v4, v4, v145
	v_mul_f32_e32 v5, v5, v146
	v_cvt_pk_bf16_f32 v4, v4, v5
	flat_store_dword v[6:7], v4 sc1
	ds_read_b64 v[4:5], v144
	s_ashr_i32 s23, s22, 31
	s_lshl_b64 s[22:23], s[22:23], 11
	v_mov_b32_e32 v6, s46
	s_waitcnt lgkmcnt(0)
	v_pk_add_f32 v[2:3], v[2:3], v[4:5] op_sel_hi:[1,0] neg_lo:[0,1] neg_hi:[0,1]
	s_nop 0
	v_pk_mul_f32 v[2:3], v[4:5], v[2:3] op_sel:[1,0]
	s_nop 0
	v_pk_fma_f32 v[2:3], v[140:141], v[2:3], v[142:143]
	s_nop 0
	v_mul_f32_e32 v4, 0xbfb8aa3b, v2
	v_mul_f32_e32 v5, 0xbfb8aa3b, v3
	v_exp_f32_e32 v4, v4
	v_exp_f32_e32 v5, v5
	v_add_f32_e32 v4, 1.0, v4
	v_add_f32_e32 v5, 1.0, v5
	v_rcp_f32_e32 v7, v4
	v_rcp_f32_e32 v144, v5
	v_lshl_add_u64 v[4:5], v[78:79], 0, s[22:23]
	s_add_i32 s22, s36, 3
	v_mul_f32_e32 v2, v2, v7
	v_mul_f32_e32 v3, v3, v144
	v_cvt_pk_bf16_f32 v2, v2, v3
	flat_store_dword v[4:5], v2 sc1
	ds_read_b64 v[2:3], v6
	s_ashr_i32 s23, s22, 31
	s_lshl_b64 s[22:23], s[22:23], 11
	v_mov_b32_e32 v6, s47
	s_waitcnt lgkmcnt(0)
	v_pk_add_f32 v[4:5], v[8:9], v[2:3] op_sel_hi:[1,0] neg_lo:[0,1] neg_hi:[0,1]
	s_nop 0
	v_pk_mul_f32 v[2:3], v[2:3], v[4:5] op_sel:[1,0]
	s_nop 0
	v_pk_fma_f32 v[2:3], v[140:141], v[2:3], v[142:143]
	s_nop 0
	v_mul_f32_e32 v4, 0xbfb8aa3b, v2
	v_mul_f32_e32 v5, 0xbfb8aa3b, v3
	v_exp_f32_e32 v4, v4
	v_exp_f32_e32 v5, v5
	v_add_f32_e32 v4, 1.0, v4
	v_add_f32_e32 v5, 1.0, v5
	v_rcp_f32_e32 v7, v4
	v_rcp_f32_e32 v8, v5
	v_lshl_add_u64 v[4:5], v[78:79], 0, s[22:23]
	s_add_i32 s22, s36, 4
	v_mul_f32_e32 v2, v2, v7
	v_mul_f32_e32 v3, v3, v8
	v_cvt_pk_bf16_f32 v2, v2, v3
	flat_store_dword v[4:5], v2 sc1
	ds_read_b64 v[2:3], v6
	s_ashr_i32 s23, s22, 31
	s_lshl_b64 s[22:23], s[22:23], 11
	v_mov_b32_e32 v6, s48
	s_waitcnt lgkmcnt(0)
	v_pk_add_f32 v[4:5], v[10:11], v[2:3] op_sel_hi:[1,0] neg_lo:[0,1] neg_hi:[0,1]
	s_nop 0
	v_pk_mul_f32 v[2:3], v[2:3], v[4:5] op_sel:[1,0]
	s_nop 0
	v_pk_fma_f32 v[2:3], v[140:141], v[2:3], v[142:143]
	s_nop 0
	v_mul_f32_e32 v4, 0xbfb8aa3b, v2
	v_mul_f32_e32 v5, 0xbfb8aa3b, v3
	v_exp_f32_e32 v4, v4
	v_exp_f32_e32 v5, v5
	v_add_f32_e32 v4, 1.0, v4
	v_add_f32_e32 v5, 1.0, v5
	v_rcp_f32_e32 v7, v4
	v_rcp_f32_e32 v8, v5
	v_lshl_add_u64 v[4:5], v[78:79], 0, s[22:23]
	s_add_i32 s22, s36, 5
	v_mul_f32_e32 v2, v2, v7
	v_mul_f32_e32 v3, v3, v8
	v_cvt_pk_bf16_f32 v2, v2, v3
	flat_store_dword v[4:5], v2 sc1
	ds_read_b64 v[2:3], v6
	s_ashr_i32 s23, s22, 31
	s_lshl_b64 s[22:23], s[22:23], 11
	v_mov_b32_e32 v6, s49
	s_waitcnt lgkmcnt(0)
	v_pk_add_f32 v[4:5], v[12:13], v[2:3] op_sel_hi:[1,0] neg_lo:[0,1] neg_hi:[0,1]
	s_nop 0
	v_pk_mul_f32 v[2:3], v[2:3], v[4:5] op_sel:[1,0]
	s_nop 0
	v_pk_fma_f32 v[2:3], v[140:141], v[2:3], v[142:143]
	s_nop 0
	v_mul_f32_e32 v4, 0xbfb8aa3b, v2
	v_mul_f32_e32 v5, 0xbfb8aa3b, v3
	v_exp_f32_e32 v4, v4
	v_exp_f32_e32 v5, v5
	v_add_f32_e32 v4, 1.0, v4
	v_add_f32_e32 v5, 1.0, v5
	v_rcp_f32_e32 v7, v4
	v_rcp_f32_e32 v8, v5
	v_lshl_add_u64 v[4:5], v[78:79], 0, s[22:23]
	s_add_i32 s22, s36, 6
	v_mul_f32_e32 v2, v2, v7
	v_mul_f32_e32 v3, v3, v8
	v_cvt_pk_bf16_f32 v2, v2, v3
	flat_store_dword v[4:5], v2 sc1
	ds_read_b64 v[2:3], v6
	s_ashr_i32 s23, s22, 31
	s_lshl_b64 s[22:23], s[22:23], 11
	v_mov_b32_e32 v6, s50
	s_waitcnt lgkmcnt(0)
	v_pk_add_f32 v[4:5], v[14:15], v[2:3] op_sel_hi:[1,0] neg_lo:[0,1] neg_hi:[0,1]
	s_nop 0
	v_pk_mul_f32 v[2:3], v[2:3], v[4:5] op_sel:[1,0]
	s_nop 0
	v_pk_fma_f32 v[2:3], v[140:141], v[2:3], v[142:143]
	s_nop 0
	v_mul_f32_e32 v4, 0xbfb8aa3b, v2
	v_mul_f32_e32 v5, 0xbfb8aa3b, v3
	v_exp_f32_e32 v4, v4
	v_exp_f32_e32 v5, v5
	v_add_f32_e32 v4, 1.0, v4
	v_add_f32_e32 v5, 1.0, v5
	v_rcp_f32_e32 v7, v4
	v_rcp_f32_e32 v8, v5
	v_lshl_add_u64 v[4:5], v[78:79], 0, s[22:23]
	s_add_i32 s22, s36, 7
	v_mul_f32_e32 v2, v2, v7
	v_mul_f32_e32 v3, v3, v8
	v_cvt_pk_bf16_f32 v2, v2, v3
	flat_store_dword v[4:5], v2 sc1
	ds_read_b64 v[2:3], v6
	s_ashr_i32 s23, s22, 31
	s_lshl_b64 s[22:23], s[22:23], 11
	v_mov_b32_e32 v6, s51
	s_waitcnt lgkmcnt(0)
	v_pk_add_f32 v[4:5], v[16:17], v[2:3] op_sel_hi:[1,0] neg_lo:[0,1] neg_hi:[0,1]
	s_nop 0
	v_pk_mul_f32 v[2:3], v[2:3], v[4:5] op_sel:[1,0]
	s_nop 0
	v_pk_fma_f32 v[2:3], v[140:141], v[2:3], v[142:143]
	s_nop 0
	v_mul_f32_e32 v4, 0xbfb8aa3b, v2
	v_mul_f32_e32 v5, 0xbfb8aa3b, v3
	v_exp_f32_e32 v4, v4
	v_exp_f32_e32 v5, v5
	v_add_f32_e32 v4, 1.0, v4
	v_add_f32_e32 v5, 1.0, v5
	v_rcp_f32_e32 v7, v4
	v_rcp_f32_e32 v8, v5
	v_lshl_add_u64 v[4:5], v[78:79], 0, s[22:23]
	s_add_i32 s22, s36, 8
	v_mul_f32_e32 v2, v2, v7
	v_mul_f32_e32 v3, v3, v8
	v_cvt_pk_bf16_f32 v2, v2, v3
	flat_store_dword v[4:5], v2 sc1
	ds_read_b64 v[2:3], v6
	s_ashr_i32 s23, s22, 31
	s_lshl_b64 s[22:23], s[22:23], 11
	v_mov_b32_e32 v6, s52
	s_waitcnt lgkmcnt(0)
	v_pk_add_f32 v[4:5], v[18:19], v[2:3] op_sel_hi:[1,0] neg_lo:[0,1] neg_hi:[0,1]
	s_nop 0
	v_pk_mul_f32 v[2:3], v[2:3], v[4:5] op_sel:[1,0]
	s_nop 0
	v_pk_fma_f32 v[2:3], v[140:141], v[2:3], v[142:143]
	s_nop 0
	v_mul_f32_e32 v4, 0xbfb8aa3b, v2
	v_mul_f32_e32 v5, 0xbfb8aa3b, v3
	v_exp_f32_e32 v4, v4
	v_exp_f32_e32 v5, v5
	v_add_f32_e32 v4, 1.0, v4
	v_add_f32_e32 v5, 1.0, v5
	v_rcp_f32_e32 v7, v4
	v_rcp_f32_e32 v8, v5
	v_lshl_add_u64 v[4:5], v[78:79], 0, s[22:23]
	s_add_i32 s22, s36, 9
	v_mul_f32_e32 v2, v2, v7
	v_mul_f32_e32 v3, v3, v8
	v_cvt_pk_bf16_f32 v2, v2, v3
	flat_store_dword v[4:5], v2 sc1
	ds_read_b64 v[2:3], v6
	s_ashr_i32 s23, s22, 31
	s_lshl_b64 s[22:23], s[22:23], 11
	v_mov_b32_e32 v6, s53
	s_waitcnt lgkmcnt(0)
	v_pk_add_f32 v[4:5], v[22:23], v[2:3] op_sel_hi:[1,0] neg_lo:[0,1] neg_hi:[0,1]
	s_nop 0
	v_pk_mul_f32 v[2:3], v[2:3], v[4:5] op_sel:[1,0]
	s_nop 0
	v_pk_fma_f32 v[2:3], v[140:141], v[2:3], v[142:143]
	s_nop 0
	v_mul_f32_e32 v4, 0xbfb8aa3b, v2
	v_mul_f32_e32 v5, 0xbfb8aa3b, v3
	v_exp_f32_e32 v4, v4
	v_exp_f32_e32 v5, v5
	v_add_f32_e32 v4, 1.0, v4
	v_add_f32_e32 v5, 1.0, v5
	v_rcp_f32_e32 v7, v4
	v_rcp_f32_e32 v8, v5
	v_lshl_add_u64 v[4:5], v[78:79], 0, s[22:23]
	s_add_i32 s22, s36, 10
	v_mul_f32_e32 v2, v2, v7
	v_mul_f32_e32 v3, v3, v8
	v_cvt_pk_bf16_f32 v2, v2, v3
	flat_store_dword v[4:5], v2 sc1
	ds_read_b64 v[2:3], v6
	s_ashr_i32 s23, s22, 31
	s_lshl_b64 s[22:23], s[22:23], 11
	v_mov_b32_e32 v6, s54
	s_waitcnt lgkmcnt(0)
	v_pk_add_f32 v[4:5], v[20:21], v[2:3] op_sel_hi:[1,0] neg_lo:[0,1] neg_hi:[0,1]
	s_nop 0
	v_pk_mul_f32 v[2:3], v[2:3], v[4:5] op_sel:[1,0]
	s_nop 0
	v_pk_fma_f32 v[2:3], v[140:141], v[2:3], v[142:143]
	s_nop 0
	v_mul_f32_e32 v4, 0xbfb8aa3b, v2
	v_mul_f32_e32 v5, 0xbfb8aa3b, v3
	v_exp_f32_e32 v4, v4
	v_exp_f32_e32 v5, v5
	v_add_f32_e32 v4, 1.0, v4
	v_add_f32_e32 v5, 1.0, v5
	v_rcp_f32_e32 v7, v4
	v_rcp_f32_e32 v8, v5
	v_lshl_add_u64 v[4:5], v[78:79], 0, s[22:23]
	s_add_i32 s22, s36, 11
	v_mul_f32_e32 v2, v2, v7
	v_mul_f32_e32 v3, v3, v8
	v_cvt_pk_bf16_f32 v2, v2, v3
	flat_store_dword v[4:5], v2 sc1
	ds_read_b64 v[2:3], v6
	s_ashr_i32 s23, s22, 31
	s_lshl_b64 s[22:23], s[22:23], 11
	v_mov_b32_e32 v6, s55
	s_waitcnt lgkmcnt(0)
	v_pk_add_f32 v[4:5], v[24:25], v[2:3] op_sel_hi:[1,0] neg_lo:[0,1] neg_hi:[0,1]
	s_nop 0
	v_pk_mul_f32 v[2:3], v[2:3], v[4:5] op_sel:[1,0]
	s_nop 0
	v_pk_fma_f32 v[2:3], v[140:141], v[2:3], v[142:143]
	s_nop 0
	v_mul_f32_e32 v4, 0xbfb8aa3b, v2
	v_mul_f32_e32 v5, 0xbfb8aa3b, v3
	v_exp_f32_e32 v4, v4
	v_exp_f32_e32 v5, v5
	v_add_f32_e32 v4, 1.0, v4
	v_add_f32_e32 v5, 1.0, v5
	v_rcp_f32_e32 v7, v4
	v_rcp_f32_e32 v8, v5
	v_lshl_add_u64 v[4:5], v[78:79], 0, s[22:23]
	s_add_i32 s22, s36, 12
	v_mul_f32_e32 v2, v2, v7
	v_mul_f32_e32 v3, v3, v8
	v_cvt_pk_bf16_f32 v2, v2, v3
	flat_store_dword v[4:5], v2 sc1
	ds_read_b64 v[2:3], v6
	s_ashr_i32 s23, s22, 31
	s_lshl_b64 s[22:23], s[22:23], 11
	v_mov_b32_e32 v6, s56
	s_waitcnt lgkmcnt(0)
	v_pk_add_f32 v[4:5], v[26:27], v[2:3] op_sel_hi:[1,0] neg_lo:[0,1] neg_hi:[0,1]
	s_nop 0
	v_pk_mul_f32 v[2:3], v[2:3], v[4:5] op_sel:[1,0]
	s_nop 0
	v_pk_fma_f32 v[2:3], v[140:141], v[2:3], v[142:143]
	s_nop 0
	v_mul_f32_e32 v4, 0xbfb8aa3b, v2
	v_mul_f32_e32 v5, 0xbfb8aa3b, v3
	v_exp_f32_e32 v4, v4
	v_exp_f32_e32 v5, v5
	v_add_f32_e32 v4, 1.0, v4
	v_add_f32_e32 v5, 1.0, v5
	v_rcp_f32_e32 v7, v4
	v_rcp_f32_e32 v8, v5
	v_lshl_add_u64 v[4:5], v[78:79], 0, s[22:23]
	s_add_i32 s22, s36, 13
	v_mul_f32_e32 v2, v2, v7
	v_mul_f32_e32 v3, v3, v8
	v_cvt_pk_bf16_f32 v2, v2, v3
	flat_store_dword v[4:5], v2 sc1
	ds_read_b64 v[2:3], v6
	s_ashr_i32 s23, s22, 31
	s_lshl_b64 s[22:23], s[22:23], 11
	v_mov_b32_e32 v6, s57
	s_waitcnt lgkmcnt(0)
	v_pk_add_f32 v[4:5], v[28:29], v[2:3] op_sel_hi:[1,0] neg_lo:[0,1] neg_hi:[0,1]
	s_nop 0
	v_pk_mul_f32 v[2:3], v[2:3], v[4:5] op_sel:[1,0]
	s_nop 0
	v_pk_fma_f32 v[2:3], v[140:141], v[2:3], v[142:143]
	s_nop 0
	v_mul_f32_e32 v4, 0xbfb8aa3b, v2
	v_mul_f32_e32 v5, 0xbfb8aa3b, v3
	v_exp_f32_e32 v4, v4
	v_exp_f32_e32 v5, v5
	v_add_f32_e32 v4, 1.0, v4
	v_add_f32_e32 v5, 1.0, v5
	v_rcp_f32_e32 v7, v4
	v_rcp_f32_e32 v8, v5
	v_lshl_add_u64 v[4:5], v[78:79], 0, s[22:23]
	s_add_i32 s22, s36, 14
	v_mul_f32_e32 v2, v2, v7
	v_mul_f32_e32 v3, v3, v8
	v_cvt_pk_bf16_f32 v2, v2, v3
	flat_store_dword v[4:5], v2 sc1
	ds_read_b64 v[2:3], v6
	s_ashr_i32 s23, s22, 31
	s_lshl_b64 s[22:23], s[22:23], 11
	v_mov_b32_e32 v6, s58
	s_waitcnt lgkmcnt(0)
	v_pk_add_f32 v[4:5], v[30:31], v[2:3] op_sel_hi:[1,0] neg_lo:[0,1] neg_hi:[0,1]
	s_nop 0
	v_pk_mul_f32 v[2:3], v[2:3], v[4:5] op_sel:[1,0]
	s_nop 0
	v_pk_fma_f32 v[2:3], v[140:141], v[2:3], v[142:143]
	s_nop 0
	v_mul_f32_e32 v4, 0xbfb8aa3b, v2
	v_mul_f32_e32 v5, 0xbfb8aa3b, v3
	v_exp_f32_e32 v4, v4
	v_exp_f32_e32 v5, v5
	v_add_f32_e32 v4, 1.0, v4
	v_add_f32_e32 v5, 1.0, v5
	v_rcp_f32_e32 v7, v4
	v_rcp_f32_e32 v8, v5
	v_lshl_add_u64 v[4:5], v[78:79], 0, s[22:23]
	s_add_i32 s22, s36, 15
	v_mul_f32_e32 v2, v2, v7
	v_mul_f32_e32 v3, v3, v8
	v_cvt_pk_bf16_f32 v2, v2, v3
	flat_store_dword v[4:5], v2 sc1
	ds_read_b64 v[2:3], v6
	s_ashr_i32 s23, s22, 31
	s_lshl_b64 s[22:23], s[22:23], 11
	v_mov_b32_e32 v6, s59
	s_waitcnt lgkmcnt(0)
	v_pk_add_f32 v[4:5], v[32:33], v[2:3] op_sel_hi:[1,0] neg_lo:[0,1] neg_hi:[0,1]
	s_nop 0
	v_pk_mul_f32 v[2:3], v[2:3], v[4:5] op_sel:[1,0]
	s_nop 0
	v_pk_fma_f32 v[2:3], v[140:141], v[2:3], v[142:143]
	s_nop 0
	v_mul_f32_e32 v4, 0xbfb8aa3b, v2
	v_mul_f32_e32 v5, 0xbfb8aa3b, v3
	v_exp_f32_e32 v4, v4
	v_exp_f32_e32 v5, v5
	v_add_f32_e32 v4, 1.0, v4
	v_add_f32_e32 v5, 1.0, v5
	v_rcp_f32_e32 v7, v4
	v_rcp_f32_e32 v8, v5
	v_lshl_add_u64 v[4:5], v[78:79], 0, s[22:23]
	s_add_i32 s22, s36, 16
	v_mul_f32_e32 v2, v2, v7
	v_mul_f32_e32 v3, v3, v8
	v_cvt_pk_bf16_f32 v2, v2, v3
	flat_store_dword v[4:5], v2 sc1
	ds_read_b64 v[2:3], v6
	s_ashr_i32 s23, s22, 31
	s_lshl_b64 s[22:23], s[22:23], 11
	v_mov_b32_e32 v6, s60
	s_waitcnt lgkmcnt(0)
	v_pk_add_f32 v[4:5], v[34:35], v[2:3] op_sel_hi:[1,0] neg_lo:[0,1] neg_hi:[0,1]
	s_nop 0
	v_pk_mul_f32 v[2:3], v[2:3], v[4:5] op_sel:[1,0]
	s_nop 0
	v_pk_fma_f32 v[2:3], v[140:141], v[2:3], v[142:143]
	s_nop 0
	v_mul_f32_e32 v4, 0xbfb8aa3b, v2
	v_mul_f32_e32 v5, 0xbfb8aa3b, v3
	v_exp_f32_e32 v4, v4
	v_exp_f32_e32 v5, v5
	v_add_f32_e32 v4, 1.0, v4
	v_add_f32_e32 v5, 1.0, v5
	v_rcp_f32_e32 v7, v4
	v_rcp_f32_e32 v8, v5
	v_lshl_add_u64 v[4:5], v[78:79], 0, s[22:23]
	s_add_i32 s22, s36, 17
	v_mul_f32_e32 v2, v2, v7
	v_mul_f32_e32 v3, v3, v8
	v_cvt_pk_bf16_f32 v2, v2, v3
	flat_store_dword v[4:5], v2 sc1
	ds_read_b64 v[2:3], v6
	s_ashr_i32 s23, s22, 31
	s_lshl_b64 s[22:23], s[22:23], 11
	v_mov_b32_e32 v6, s61
	s_waitcnt lgkmcnt(0)
	v_pk_add_f32 v[4:5], v[40:41], v[2:3] op_sel_hi:[1,0] neg_lo:[0,1] neg_hi:[0,1]
	s_nop 0
	v_pk_mul_f32 v[2:3], v[2:3], v[4:5] op_sel:[1,0]
	s_nop 0
	v_pk_fma_f32 v[2:3], v[140:141], v[2:3], v[142:143]
	s_nop 0
	v_mul_f32_e32 v4, 0xbfb8aa3b, v2
	v_mul_f32_e32 v5, 0xbfb8aa3b, v3
	v_exp_f32_e32 v4, v4
	v_exp_f32_e32 v5, v5
	v_add_f32_e32 v4, 1.0, v4
	v_add_f32_e32 v5, 1.0, v5
	v_rcp_f32_e32 v7, v4
	v_rcp_f32_e32 v8, v5
	v_lshl_add_u64 v[4:5], v[78:79], 0, s[22:23]
	s_add_i32 s22, s36, 18
	v_mul_f32_e32 v2, v2, v7
	v_mul_f32_e32 v3, v3, v8
	v_cvt_pk_bf16_f32 v2, v2, v3
	flat_store_dword v[4:5], v2 sc1
	ds_read_b64 v[2:3], v6
	s_ashr_i32 s23, s22, 31
	s_lshl_b64 s[22:23], s[22:23], 11
	v_mov_b32_e32 v6, s62
	s_waitcnt lgkmcnt(0)
	v_pk_add_f32 v[4:5], v[38:39], v[2:3] op_sel_hi:[1,0] neg_lo:[0,1] neg_hi:[0,1]
	s_nop 0
	v_pk_mul_f32 v[2:3], v[2:3], v[4:5] op_sel:[1,0]
	s_nop 0
	v_pk_fma_f32 v[2:3], v[140:141], v[2:3], v[142:143]
	s_nop 0
	v_mul_f32_e32 v4, 0xbfb8aa3b, v2
	v_mul_f32_e32 v5, 0xbfb8aa3b, v3
	v_exp_f32_e32 v4, v4
	v_exp_f32_e32 v5, v5
	v_add_f32_e32 v4, 1.0, v4
	v_add_f32_e32 v5, 1.0, v5
	v_rcp_f32_e32 v7, v4
	v_rcp_f32_e32 v8, v5
	v_lshl_add_u64 v[4:5], v[78:79], 0, s[22:23]
	s_add_i32 s22, s36, 19
	v_mul_f32_e32 v2, v2, v7
	v_mul_f32_e32 v3, v3, v8
	v_cvt_pk_bf16_f32 v2, v2, v3
	flat_store_dword v[4:5], v2 sc1
	ds_read_b64 v[2:3], v6
	s_ashr_i32 s23, s22, 31
	s_lshl_b64 s[22:23], s[22:23], 11
	v_mov_b32_e32 v6, s63
	s_waitcnt lgkmcnt(0)
	v_pk_add_f32 v[4:5], v[36:37], v[2:3] op_sel_hi:[1,0] neg_lo:[0,1] neg_hi:[0,1]
	s_nop 0
	v_pk_mul_f32 v[2:3], v[2:3], v[4:5] op_sel:[1,0]
	s_nop 0
	v_pk_fma_f32 v[2:3], v[140:141], v[2:3], v[142:143]
	s_nop 0
	v_mul_f32_e32 v4, 0xbfb8aa3b, v2
	v_mul_f32_e32 v5, 0xbfb8aa3b, v3
	v_exp_f32_e32 v4, v4
	v_exp_f32_e32 v5, v5
	v_add_f32_e32 v4, 1.0, v4
	v_add_f32_e32 v5, 1.0, v5
	v_rcp_f32_e32 v7, v4
	v_rcp_f32_e32 v8, v5
	v_lshl_add_u64 v[4:5], v[78:79], 0, s[22:23]
	s_add_i32 s22, s36, 20
	v_mul_f32_e32 v2, v2, v7
	v_mul_f32_e32 v3, v3, v8
	v_cvt_pk_bf16_f32 v2, v2, v3
	flat_store_dword v[4:5], v2 sc1
	ds_read_b64 v[2:3], v6
	s_ashr_i32 s23, s22, 31
	s_lshl_b64 s[22:23], s[22:23], 11
	v_mov_b32_e32 v6, s64
	s_waitcnt lgkmcnt(0)
	v_pk_add_f32 v[4:5], v[42:43], v[2:3] op_sel_hi:[1,0] neg_lo:[0,1] neg_hi:[0,1]
	s_nop 0
	v_pk_mul_f32 v[2:3], v[2:3], v[4:5] op_sel:[1,0]
	s_nop 0
	v_pk_fma_f32 v[2:3], v[140:141], v[2:3], v[142:143]
	s_nop 0
	v_mul_f32_e32 v4, 0xbfb8aa3b, v2
	v_mul_f32_e32 v5, 0xbfb8aa3b, v3
	v_exp_f32_e32 v4, v4
	v_exp_f32_e32 v5, v5
	v_add_f32_e32 v4, 1.0, v4
	v_add_f32_e32 v5, 1.0, v5
	v_rcp_f32_e32 v7, v4
	v_rcp_f32_e32 v8, v5
	v_lshl_add_u64 v[4:5], v[78:79], 0, s[22:23]
	s_add_i32 s22, s36, 21
	v_mul_f32_e32 v2, v2, v7
	v_mul_f32_e32 v3, v3, v8
	v_cvt_pk_bf16_f32 v2, v2, v3
	flat_store_dword v[4:5], v2 sc1
	ds_read_b64 v[2:3], v6
	s_ashr_i32 s23, s22, 31
	s_lshl_b64 s[22:23], s[22:23], 11
	v_mov_b32_e32 v6, s65
	s_waitcnt lgkmcnt(0)
	v_pk_add_f32 v[4:5], v[44:45], v[2:3] op_sel_hi:[1,0] neg_lo:[0,1] neg_hi:[0,1]
	s_nop 0
	v_pk_mul_f32 v[2:3], v[2:3], v[4:5] op_sel:[1,0]
	s_nop 0
	v_pk_fma_f32 v[2:3], v[140:141], v[2:3], v[142:143]
	s_nop 0
	v_mul_f32_e32 v4, 0xbfb8aa3b, v2
	v_mul_f32_e32 v5, 0xbfb8aa3b, v3
	v_exp_f32_e32 v4, v4
	v_exp_f32_e32 v5, v5
	v_add_f32_e32 v4, 1.0, v4
	v_add_f32_e32 v5, 1.0, v5
	v_rcp_f32_e32 v7, v4
	v_rcp_f32_e32 v8, v5
	v_lshl_add_u64 v[4:5], v[78:79], 0, s[22:23]
	s_add_i32 s22, s36, 22
	v_mul_f32_e32 v2, v2, v7
	v_mul_f32_e32 v3, v3, v8
	v_cvt_pk_bf16_f32 v2, v2, v3
	flat_store_dword v[4:5], v2 sc1
	ds_read_b64 v[2:3], v6
	s_ashr_i32 s23, s22, 31
	s_lshl_b64 s[22:23], s[22:23], 11
	v_mov_b32_e32 v6, s66
	s_waitcnt lgkmcnt(0)
	v_pk_add_f32 v[4:5], v[46:47], v[2:3] op_sel_hi:[1,0] neg_lo:[0,1] neg_hi:[0,1]
	s_nop 0
	v_pk_mul_f32 v[2:3], v[2:3], v[4:5] op_sel:[1,0]
	s_nop 0
	v_pk_fma_f32 v[2:3], v[140:141], v[2:3], v[142:143]
	s_nop 0
	v_mul_f32_e32 v4, 0xbfb8aa3b, v2
	v_mul_f32_e32 v5, 0xbfb8aa3b, v3
	v_exp_f32_e32 v4, v4
	v_exp_f32_e32 v5, v5
	v_add_f32_e32 v4, 1.0, v4
	v_add_f32_e32 v5, 1.0, v5
	v_rcp_f32_e32 v7, v4
	v_rcp_f32_e32 v8, v5
	v_lshl_add_u64 v[4:5], v[78:79], 0, s[22:23]
	s_add_i32 s22, s36, 23
	v_mul_f32_e32 v2, v2, v7
	v_mul_f32_e32 v3, v3, v8
	v_cvt_pk_bf16_f32 v2, v2, v3
	flat_store_dword v[4:5], v2 sc1
	ds_read_b64 v[2:3], v6
	s_ashr_i32 s23, s22, 31
	s_lshl_b64 s[22:23], s[22:23], 11
	v_mov_b32_e32 v6, s67
	s_waitcnt lgkmcnt(0)
	v_pk_add_f32 v[4:5], v[48:49], v[2:3] op_sel_hi:[1,0] neg_lo:[0,1] neg_hi:[0,1]
	s_nop 0
	v_pk_mul_f32 v[2:3], v[2:3], v[4:5] op_sel:[1,0]
	s_nop 0
	v_pk_fma_f32 v[2:3], v[140:141], v[2:3], v[142:143]
	s_nop 0
	v_mul_f32_e32 v4, 0xbfb8aa3b, v2
	v_mul_f32_e32 v5, 0xbfb8aa3b, v3
	v_exp_f32_e32 v4, v4
	v_exp_f32_e32 v5, v5
	v_add_f32_e32 v4, 1.0, v4
	v_add_f32_e32 v5, 1.0, v5
	v_rcp_f32_e32 v7, v4
	v_rcp_f32_e32 v8, v5
	v_lshl_add_u64 v[4:5], v[78:79], 0, s[22:23]
	s_add_i32 s22, s36, 24
	v_mul_f32_e32 v2, v2, v7
	v_mul_f32_e32 v3, v3, v8
	v_cvt_pk_bf16_f32 v2, v2, v3
	flat_store_dword v[4:5], v2 sc1
	ds_read_b64 v[2:3], v6
	s_ashr_i32 s23, s22, 31
	s_lshl_b64 s[22:23], s[22:23], 11
	v_mov_b32_e32 v6, s68
	s_waitcnt lgkmcnt(0)
	v_pk_add_f32 v[4:5], v[50:51], v[2:3] op_sel_hi:[1,0] neg_lo:[0,1] neg_hi:[0,1]
	s_nop 0
	v_pk_mul_f32 v[2:3], v[2:3], v[4:5] op_sel:[1,0]
	s_nop 0
	v_pk_fma_f32 v[2:3], v[140:141], v[2:3], v[142:143]
	s_nop 0
	v_mul_f32_e32 v4, 0xbfb8aa3b, v2
	v_mul_f32_e32 v5, 0xbfb8aa3b, v3
	v_exp_f32_e32 v4, v4
	v_exp_f32_e32 v5, v5
	v_add_f32_e32 v4, 1.0, v4
	v_add_f32_e32 v5, 1.0, v5
	v_rcp_f32_e32 v7, v4
	v_rcp_f32_e32 v8, v5
	v_lshl_add_u64 v[4:5], v[78:79], 0, s[22:23]
	s_add_i32 s22, s36, 25
	v_mul_f32_e32 v2, v2, v7
	v_mul_f32_e32 v3, v3, v8
	v_cvt_pk_bf16_f32 v2, v2, v3
	flat_store_dword v[4:5], v2 sc1
	ds_read_b64 v[2:3], v6
	s_ashr_i32 s23, s22, 31
	s_lshl_b64 s[22:23], s[22:23], 11
	v_mov_b32_e32 v6, s69
	s_waitcnt lgkmcnt(0)
	v_pk_add_f32 v[4:5], v[62:63], v[2:3] op_sel_hi:[1,0] neg_lo:[0,1] neg_hi:[0,1]
	s_nop 0
	v_pk_mul_f32 v[2:3], v[2:3], v[4:5] op_sel:[1,0]
	s_nop 0
	v_pk_fma_f32 v[2:3], v[140:141], v[2:3], v[142:143]
	s_nop 0
	v_mul_f32_e32 v4, 0xbfb8aa3b, v2
	v_mul_f32_e32 v5, 0xbfb8aa3b, v3
	v_exp_f32_e32 v4, v4
	v_exp_f32_e32 v5, v5
	v_add_f32_e32 v4, 1.0, v4
	v_add_f32_e32 v5, 1.0, v5
	v_rcp_f32_e32 v7, v4
	v_rcp_f32_e32 v8, v5
	v_lshl_add_u64 v[4:5], v[78:79], 0, s[22:23]
	s_add_i32 s22, s36, 26
	v_mul_f32_e32 v2, v2, v7
	v_mul_f32_e32 v3, v3, v8
	v_cvt_pk_bf16_f32 v2, v2, v3
	flat_store_dword v[4:5], v2 sc1
	ds_read_b64 v[2:3], v6
	s_ashr_i32 s23, s22, 31
	s_lshl_b64 s[22:23], s[22:23], 11
	v_mov_b32_e32 v6, s73
	s_waitcnt lgkmcnt(0)
	v_pk_add_f32 v[4:5], v[56:57], v[2:3] op_sel_hi:[1,0] neg_lo:[0,1] neg_hi:[0,1]
	s_nop 0
	v_pk_mul_f32 v[2:3], v[2:3], v[4:5] op_sel:[1,0]
	s_nop 0
	v_pk_fma_f32 v[2:3], v[140:141], v[2:3], v[142:143]
	s_nop 0
	v_mul_f32_e32 v4, 0xbfb8aa3b, v2
	v_mul_f32_e32 v5, 0xbfb8aa3b, v3
	v_exp_f32_e32 v4, v4
	v_exp_f32_e32 v5, v5
	v_add_f32_e32 v4, 1.0, v4
	v_add_f32_e32 v5, 1.0, v5
	v_rcp_f32_e32 v7, v4
	v_rcp_f32_e32 v8, v5
	v_lshl_add_u64 v[4:5], v[78:79], 0, s[22:23]
	s_add_i32 s22, s36, 27
	v_mul_f32_e32 v2, v2, v7
	v_mul_f32_e32 v3, v3, v8
	v_cvt_pk_bf16_f32 v2, v2, v3
	flat_store_dword v[4:5], v2 sc1
	ds_read_b64 v[2:3], v6
	s_ashr_i32 s23, s22, 31
	s_lshl_b64 s[22:23], s[22:23], 11
	v_mov_b32_e32 v6, s74
	s_waitcnt lgkmcnt(0)
	v_pk_add_f32 v[4:5], v[52:53], v[2:3] op_sel_hi:[1,0] neg_lo:[0,1] neg_hi:[0,1]
	s_nop 0
	v_pk_mul_f32 v[2:3], v[2:3], v[4:5] op_sel:[1,0]
	s_nop 0
	v_pk_fma_f32 v[2:3], v[140:141], v[2:3], v[142:143]
	s_nop 0
	v_mul_f32_e32 v4, 0xbfb8aa3b, v2
	v_mul_f32_e32 v5, 0xbfb8aa3b, v3
	v_exp_f32_e32 v4, v4
	v_exp_f32_e32 v5, v5
	v_add_f32_e32 v4, 1.0, v4
	v_add_f32_e32 v5, 1.0, v5
	v_rcp_f32_e32 v7, v4
	v_rcp_f32_e32 v8, v5
	v_lshl_add_u64 v[4:5], v[78:79], 0, s[22:23]
	s_add_i32 s22, s36, 28
	v_mul_f32_e32 v2, v2, v7
	v_mul_f32_e32 v3, v3, v8
	v_cvt_pk_bf16_f32 v2, v2, v3
	flat_store_dword v[4:5], v2 sc1
	ds_read_b64 v[2:3], v6
	s_ashr_i32 s23, s22, 31
	s_lshl_b64 s[22:23], s[22:23], 11
	v_mov_b32_e32 v6, s75
	s_waitcnt lgkmcnt(0)
	v_pk_add_f32 v[4:5], v[60:61], v[2:3] op_sel_hi:[1,0] neg_lo:[0,1] neg_hi:[0,1]
	s_nop 0
	v_pk_mul_f32 v[2:3], v[2:3], v[4:5] op_sel:[1,0]
	s_nop 0
	v_pk_fma_f32 v[2:3], v[140:141], v[2:3], v[142:143]
	s_nop 0
	v_mul_f32_e32 v4, 0xbfb8aa3b, v2
	v_mul_f32_e32 v5, 0xbfb8aa3b, v3
	v_exp_f32_e32 v4, v4
	v_exp_f32_e32 v5, v5
	v_add_f32_e32 v4, 1.0, v4
	v_add_f32_e32 v5, 1.0, v5
	v_rcp_f32_e32 v7, v4
	v_rcp_f32_e32 v8, v5
	v_lshl_add_u64 v[4:5], v[78:79], 0, s[22:23]
	s_add_i32 s22, s36, 29
	v_mul_f32_e32 v2, v2, v7
	v_mul_f32_e32 v3, v3, v8
	v_cvt_pk_bf16_f32 v2, v2, v3
	flat_store_dword v[4:5], v2 sc1
	ds_read_b64 v[2:3], v6
	s_ashr_i32 s23, s22, 31
	s_lshl_b64 s[22:23], s[22:23], 11
	v_mov_b32_e32 v6, s76
	s_waitcnt lgkmcnt(0)
	v_pk_add_f32 v[4:5], v[58:59], v[2:3] op_sel_hi:[1,0] neg_lo:[0,1] neg_hi:[0,1]
	s_nop 0
	v_pk_mul_f32 v[2:3], v[2:3], v[4:5] op_sel:[1,0]
	s_nop 0
	v_pk_fma_f32 v[2:3], v[140:141], v[2:3], v[142:143]
	s_nop 0
	v_mul_f32_e32 v4, 0xbfb8aa3b, v2
	v_mul_f32_e32 v5, 0xbfb8aa3b, v3
	v_exp_f32_e32 v4, v4
	v_exp_f32_e32 v5, v5
	v_add_f32_e32 v4, 1.0, v4
	v_add_f32_e32 v5, 1.0, v5
	v_rcp_f32_e32 v7, v4
	v_rcp_f32_e32 v8, v5
	v_lshl_add_u64 v[4:5], v[78:79], 0, s[22:23]
	s_add_i32 s22, s36, 30
	v_mul_f32_e32 v2, v2, v7
	v_mul_f32_e32 v3, v3, v8
	v_cvt_pk_bf16_f32 v2, v2, v3
	flat_store_dword v[4:5], v2 sc1
	ds_read_b64 v[2:3], v6
	s_ashr_i32 s23, s22, 31
	s_lshl_b64 s[22:23], s[22:23], 11
	v_mov_b32_e32 v6, s77
	s_waitcnt lgkmcnt(0)
	v_pk_add_f32 v[4:5], v[54:55], v[2:3] op_sel_hi:[1,0] neg_lo:[0,1] neg_hi:[0,1]
	s_nop 0
	v_pk_mul_f32 v[2:3], v[2:3], v[4:5] op_sel:[1,0]
	s_nop 0
	v_pk_fma_f32 v[2:3], v[140:141], v[2:3], v[142:143]
	s_nop 0
	v_mul_f32_e32 v4, 0xbfb8aa3b, v2
	v_mul_f32_e32 v5, 0xbfb8aa3b, v3
	v_exp_f32_e32 v4, v4
	v_exp_f32_e32 v5, v5
	v_add_f32_e32 v4, 1.0, v4
	v_add_f32_e32 v5, 1.0, v5
	v_rcp_f32_e32 v7, v4
	v_rcp_f32_e32 v8, v5
	v_lshl_add_u64 v[4:5], v[78:79], 0, s[22:23]
	s_add_i32 s22, s36, 31
	v_mul_f32_e32 v2, v2, v7
	v_mul_f32_e32 v3, v3, v8
	v_cvt_pk_bf16_f32 v2, v2, v3
	flat_store_dword v[4:5], v2 sc1
	ds_read_b64 v[2:3], v6
	s_ashr_i32 s23, s22, 31
	s_add_i32 s36, s36, s39
	s_lshl_b64 s[22:23], s[22:23], 11
	s_cmpk_gt_i32 s78, 0xff
	s_waitcnt lgkmcnt(0)
	v_pk_add_f32 v[4:5], v[64:65], v[2:3] op_sel_hi:[1,0] neg_lo:[0,1] neg_hi:[0,1]
	s_nop 0
	v_pk_mul_f32 v[2:3], v[2:3], v[4:5] op_sel:[1,0]
	s_nop 0
	v_pk_fma_f32 v[2:3], v[140:141], v[2:3], v[142:143]
	s_nop 0
	v_mul_f32_e32 v4, 0xbfb8aa3b, v2
	v_mul_f32_e32 v5, 0xbfb8aa3b, v3
	v_exp_f32_e32 v4, v4
	v_exp_f32_e32 v5, v5
	v_add_f32_e32 v4, 1.0, v4
	v_add_f32_e32 v5, 1.0, v5
	v_rcp_f32_e32 v6, v4
	v_rcp_f32_e32 v7, v5
	v_lshl_add_u64 v[4:5], v[78:79], 0, s[22:23]
	v_mul_f32_e32 v2, v2, v6
	v_mul_f32_e32 v3, v3, v7
	v_cvt_pk_bf16_f32 v2, v2, v3
	flat_store_dword v[4:5], v2 sc1
	s_waitcnt lgkmcnt(0)
	s_barrier
	s_cbranch_scc1 .LBB0_383

.LBB0_383:
	s_waitcnt vmcnt(0)
	s_mov_b32 s11, 0
	v_cmp_eq_u32_e32 vcc, 0, v0
	s_waitcnt vmcnt(0)
	s_barrier
	s_and_saveexec_b64 s[4:5], vcc
	s_cbranch_execz .LBB0_385
	v_mov_b32_e32 v1, s34
	v_add_co_u32_e32 v2, vcc, 0x6000, v1
	v_mov_b32_e32 v1, s35
	v_addc_co_u32_e32 v3, vcc, 0, v1, vcc
	v_mov_b32_e32 v1, 1
